# gMLP spatial k-step: its 8 transposed LDS reads issued together with counted waits (was one pair per MFMA with lgkmcnt(0))
# speedup vs baseline: 1.0088x; 1.0002x over previous
; #define GAS __attribute__((address_space(1)))
; #define LAS __attribute__((address_space(3)))
; __device__ __forceinline__ bf16x8 mk8(s16x4 a, s16x4 b) { return __builtin_shufflevector(a, b, 0, 1, 2, 3, 4, 5, 6, 7); }
; #define MFMA16(a, b, c) __builtin_amdgcn_mfma_f32_16x16x32_bf16((a), (b), (c), 0, 0, 0)
; __device__ __forceinline__ s16x4 vtr_s(const LAS bf16_t* p) { return __builtin_bit_cast(s16x4, __builtin_amdgcn_ds_read_tr16_b64_v4i16((LAS v4i16s_t*)p)); }
; __device__ __forceinline__ void spatial_phase(LAS unsigned char* lds, const bf16_t* U, const bf16_t* V, const float* vssq, const float* vgain, const float* bsp, const bf16_t* Wsb, bf16_t* cat,
;                                               int tid, int lane, int wave) {
;     ...
;                 for (int ks = 0; ks <= ksmax; ++ks) {
;                     const GAS bf16_t* wp = (const GAS bf16_t*)Wsb + ((size_t)(g * 128 + t) * 128 + 32 * ks + 4 * q);
;                     const bf16x8 bfr = mk8(*(const GAS s16x4*)wp, *(const GAS s16x4*)(wp + 16));
; #pragma unroll
;                     for (int dt = 0; dt < 4; ++dt) {
;                         const LAS bf16_t* vp = vS + (32 * ks + 4 * q + (lr >> 2)) * 272 + gl * 64 + 16 * dt + 4 * (lr & 3);
;                         const bf16x8 afr = mk8(vtr_s(vp), vtr_s(vp + 16 * 272));
;                         acc[dt] = MFMA16(afr, bfr, acc[dt]);
;                     }
.LBB0_1194:
	global_load_dwordx2 v[100:101], v[60:61], off offset:-32
	global_load_dwordx2 v[102:103], v[60:61], off
	v_add_u32_e32 v99, 0xffffdda0, v98
	ds_read_b64_tr_b16 v[104:105], v99
	v_add_u32_e32 v99, 0xffffffa0, v98
	ds_read_b64_tr_b16 v[106:107], v99
	v_add_u32_e32 v99, 0xffffddc0, v98
	ds_read_b64_tr_b16 v[204:205], v99
	v_subrev_u32_e32 v99, 64, v98
	ds_read_b64_tr_b16 v[206:207], v99
	v_add_u32_e32 v99, 0xffffdde0, v98
	ds_read_b64_tr_b16 v[208:209], v99
	v_subrev_u32_e32 v99, 32, v98
	ds_read_b64_tr_b16 v[210:211], v99
	v_add_u32_e32 v99, 0xffffde00, v98
	ds_read_b64_tr_b16 v[212:213], v99
	ds_read_b64_tr_b16 v[214:215], v98
	v_add_u32_e32 v98, 0x4400, v98
	s_add_i32 s19, s19, -1
	v_lshl_add_u64 v[60:61], v[60:61], 0, 64
	s_cmp_eq_u32 s19, 0
	s_waitcnt vmcnt(0) lgkmcnt(6)
	v_mfma_f32_16x16x32_bf16 v[12:15], v[104:107], v[100:103], v[12:15]
	s_waitcnt lgkmcnt(4)
	v_mfma_f32_16x16x32_bf16 v[8:11], v[204:207], v[100:103], v[8:11]
	s_waitcnt lgkmcnt(2)
	v_mfma_f32_16x16x32_bf16 v[4:7], v[208:211], v[100:103], v[4:7]
	s_waitcnt lgkmcnt(0)
	v_mfma_f32_16x16x32_bf16 v[0:3], v[212:215], v[100:103], v[0:3]
	s_cbranch_scc0 .LBB0_1194
	s_branch .LBB0_1191
